# pool_z pipelined: next tile's rows / rstd / gains requested before the current tile is computed; per-token 1/n precomputed per lane once per tile; window rows streamed through a small register buffer
# baseline (speedup 1.0000x reference)
.Lxbn8_end:
.LBB0_1636:
	s_or_b64 exec, exec, s[12:13]
	s_mov_b64 s[12:13], s[0:1]
	s_waitcnt lgkmcnt(0)
	v_mov_b32_e32 v0, v170
	s_barrier
	s_mov_b64 s[14:15], exec
	s_load_dwordx2 s[12:13], s[0:1], 0xe8
	v_and_b32_e32 v0, 63, v170
	v_lshlrev_b32_e32 v1, 4, v0
	v_readfirstlane_b32 s34, v170
	s_lshr_b32 s34, s34, 6
	s_waitcnt lgkmcnt(0)
	s_add_u32 s16, s12, 0x46bc000
	s_addc_u32 s17, s13, 0
	s_add_u32 s18, s12, 0x76bc000
	s_addc_u32 s19, s13, 0
	s_add_u32 s20, s12, 0x780000
	s_addc_u32 s21, s13, 0
	s_add_u32 s22, s12, 0x2ebc000
	s_addc_u32 s23, s13, 0
	s_mov_b32 s24, s2
	s_and_b32 s26, s24, 3
	s_lshr_b32 s28, s24, 2
	s_lshl_b32 s28, s28, 6
	s_lshl_b32 s27, 1, s26
	s_lshl_b32 s35, s27, 1
	s_add_i32 s35, s35, 64
	s_cmp_lt_u32 s28, 0x1000
	s_cbranch_scc0 .Lpza_lat
	s_and_b32 s29, s28, 0xffffff00
	s_movk_i32 s30, 0x100
	s_mov_b32 s45, 30
	s_branch .Lpza_seq
.Lpza_lat:
	s_sub_i32 s45, s28, 0x1000
	s_and_b32 s29, s45, 0xfffff800
	s_add_i32 s29, s29, 0x1000
	s_movk_i32 s30, 0x800
	s_lshr_b32 s45, s45, 11
	s_mul_i32 s45, s45, 6
	s_add_i32 s45, s45, 36
.Lpza_seq:
	s_sub_i32 s31, s28, s29
	s_lshl_b32 s36, s26, 10
	v_add_u32_e32 v2, s36, v1
	s_add_i32 s40, s34, 0
	s_cmp_ge_u32 s40, s35
	s_cbranch_scc1 .Lpza_ld
	s_add_i32 s41, s31, s40
	s_sub_i32 s41, s41, s27
	s_max_i32 s41, s41, 0
	s_add_i32 s47, s30, -1
	s_min_i32 s41, s41, s47
	s_add_i32 s41, s41, s29
	s_lshl_b32 s41, s41, 12
	s_add_u32 s36, s16, s41
	s_addc_u32 s37, s17, 0
	global_load_dwordx4 v[92:95], v2, s[36:37]
	s_add_i32 s40, s34, 8
	s_cmp_ge_u32 s40, s35
	s_cbranch_scc1 .Lpza_ld
	s_add_i32 s41, s31, s40
	s_sub_i32 s41, s41, s27
	s_max_i32 s41, s41, 0
	s_add_i32 s47, s30, -1
	s_min_i32 s41, s41, s47
	s_add_i32 s41, s41, s29
	s_lshl_b32 s41, s41, 12
	s_add_u32 s36, s16, s41
	s_addc_u32 s37, s17, 0
	global_load_dwordx4 v[96:99], v2, s[36:37]
	s_add_i32 s40, s34, 16
	s_cmp_ge_u32 s40, s35
	s_cbranch_scc1 .Lpza_ld
	s_add_i32 s41, s31, s40
	s_sub_i32 s41, s41, s27
	s_max_i32 s41, s41, 0
	s_add_i32 s47, s30, -1
	s_min_i32 s41, s41, s47
	s_add_i32 s41, s41, s29
	s_lshl_b32 s41, s41, 12
	s_add_u32 s36, s16, s41
	s_addc_u32 s37, s17, 0
	global_load_dwordx4 v[100:103], v2, s[36:37]
	s_add_i32 s40, s34, 24
	s_cmp_ge_u32 s40, s35
	s_cbranch_scc1 .Lpza_ld
	s_add_i32 s41, s31, s40
	s_sub_i32 s41, s41, s27
	s_max_i32 s41, s41, 0
	s_add_i32 s47, s30, -1
	s_min_i32 s41, s41, s47
	s_add_i32 s41, s41, s29
	s_lshl_b32 s41, s41, 12
	s_add_u32 s36, s16, s41
	s_addc_u32 s37, s17, 0
	global_load_dwordx4 v[104:107], v2, s[36:37]
	s_add_i32 s40, s34, 32
	s_cmp_ge_u32 s40, s35
	s_cbranch_scc1 .Lpza_ld
	s_add_i32 s41, s31, s40
	s_sub_i32 s41, s41, s27
	s_max_i32 s41, s41, 0
	s_add_i32 s47, s30, -1
	s_min_i32 s41, s41, s47
	s_add_i32 s41, s41, s29
	s_lshl_b32 s41, s41, 12
	s_add_u32 s36, s16, s41
	s_addc_u32 s37, s17, 0
	global_load_dwordx4 v[108:111], v2, s[36:37]
	s_add_i32 s40, s34, 40
	s_cmp_ge_u32 s40, s35
	s_cbranch_scc1 .Lpza_ld
	s_add_i32 s41, s31, s40
	s_sub_i32 s41, s41, s27
	s_max_i32 s41, s41, 0
	s_add_i32 s47, s30, -1
	s_min_i32 s41, s41, s47
	s_add_i32 s41, s41, s29
	s_lshl_b32 s41, s41, 12
	s_add_u32 s36, s16, s41
	s_addc_u32 s37, s17, 0
	global_load_dwordx4 v[112:115], v2, s[36:37]
	s_add_i32 s40, s34, 48
	s_cmp_ge_u32 s40, s35
	s_cbranch_scc1 .Lpza_ld
	s_add_i32 s41, s31, s40
	s_sub_i32 s41, s41, s27
	s_max_i32 s41, s41, 0
	s_add_i32 s47, s30, -1
	s_min_i32 s41, s41, s47
	s_add_i32 s41, s41, s29
	s_lshl_b32 s41, s41, 12
	s_add_u32 s36, s16, s41
	s_addc_u32 s37, s17, 0
	global_load_dwordx4 v[116:119], v2, s[36:37]
	s_add_i32 s40, s34, 56
	s_cmp_ge_u32 s40, s35
	s_cbranch_scc1 .Lpza_ld
	s_add_i32 s41, s31, s40
	s_sub_i32 s41, s41, s27
	s_max_i32 s41, s41, 0
	s_add_i32 s47, s30, -1
	s_min_i32 s41, s41, s47
	s_add_i32 s41, s41, s29
	s_lshl_b32 s41, s41, 12
	s_add_u32 s36, s16, s41
	s_addc_u32 s37, s17, 0
	global_load_dwordx4 v[120:123], v2, s[36:37]
	s_add_i32 s40, s34, 64
	s_cmp_ge_u32 s40, s35
	s_cbranch_scc1 .Lpza_ld
	s_add_i32 s41, s31, s40
	s_sub_i32 s41, s41, s27
	s_max_i32 s41, s41, 0
	s_add_i32 s47, s30, -1
	s_min_i32 s41, s41, s47
	s_add_i32 s41, s41, s29
	s_lshl_b32 s41, s41, 12
	s_add_u32 s36, s16, s41
	s_addc_u32 s37, s17, 0
	global_load_dwordx4 v[124:127], v2, s[36:37]
	s_add_i32 s40, s34, 72
	s_cmp_ge_u32 s40, s35
	s_cbranch_scc1 .Lpza_ld
	s_add_i32 s41, s31, s40
	s_sub_i32 s41, s41, s27
	s_max_i32 s41, s41, 0
	s_add_i32 s47, s30, -1
	s_min_i32 s41, s41, s47
	s_add_i32 s41, s41, s29
	s_lshl_b32 s41, s41, 12
	s_add_u32 s36, s16, s41
	s_addc_u32 s37, s17, 0
	global_load_dwordx4 v[128:131], v2, s[36:37]
.Lpza_ld:
	s_lshl_b32 s36, s45, 12
	v_add_u32_e32 v3, s36, v2
	global_load_dwordx4 v[18:21], v3, s[20:21]
	s_lshl_b32 s41, s34, 3
	s_add_i32 s41, s41, s31
	s_sub_i32 s41, s41, s27
	v_add_u32_e32 v3, s41, v0
	v_cmp_le_i32_e64 s[36:37], 0, v3
	v_cmp_gt_i32_e64 s[12:13], s30, v3
	s_and_b64 s[36:37], s[36:37], s[12:13]
	v_max_i32_e32 v14, 0, v3
	s_add_i32 s41, s30, -1
	v_min_i32_e32 v14, s41, v14
	v_add_u32_e32 v14, s29, v14
	v_lshlrev_b32_e32 v14, 2, v14
	global_load_dword v14, v14, s[18:19]
	s_lshl_b32 s41, s34, 3
	s_add_i32 s41, s41, 4
	s_add_i32 s41, s41, s31
	s_sub_i32 s41, s41, s27
	v_add_u32_e32 v3, s41, v0
	v_cmp_le_i32_e64 s[36:37], 0, v3
	v_cmp_gt_i32_e64 s[12:13], s30, v3
	s_and_b64 s[36:37], s[36:37], s[12:13]
	v_max_i32_e32 v15, 0, v3
	s_add_i32 s41, s30, -1
	v_min_i32_e32 v15, s41, v15
	v_add_u32_e32 v15, s29, v15
	v_lshlrev_b32_e32 v15, 2, v15
	global_load_dword v15, v15, s[18:19]
	s_lshl_b32 s36, s28, 11
	s_lshl_b32 s37, s26, 9
	s_add_i32 s36, s36, s37
	v_lshl_add_u32 v16, v0, 3, s36
	v_add_u32_e32 v3, s31, v0
	v_add_u32_e32 v33, s27, v3
	v_min_u32_e32 v33, s30, v33
	v_subrev_u32_e32 v34, s27, v3
	v_max_i32_e32 v34, 0, v34
	v_sub_u32_e32 v33, v33, v34
	v_cvt_f32_i32_e32 v33, v33
	v_div_scale_f32 v34, s[12:13], v33, v33, 1.0
	v_rcp_f32_e32 v35, v34
	v_div_scale_f32 v36, vcc, 1.0, v33, 1.0
	s_nop 0
	v_fma_f32 v38, -v34, v35, 1.0
	v_fmac_f32_e32 v35, v38, v35
	v_mul_f32_e32 v37, v36, v35
	v_fma_f32 v38, -v34, v37, v36
	v_fmac_f32_e32 v37, v38, v35
	v_fma_f32 v34, -v34, v37, v36
	v_div_fmas_f32 v34, v34, v35, v37
	v_div_fixup_f32 v17, v34, v33, 1.0
.Lpz_tile:
	s_waitcnt vmcnt(0)
	s_add_i32 s40, s34, 0
	s_cmp_ge_u32 s40, s35
	s_cbranch_scc1 .Lpzb_filled
	s_lshl_b32 s40, s40, 10
	v_add_u32_e32 v4, s40, v1
	ds_write_b128 v4, v[92:95]
	s_add_i32 s40, s34, 8
	s_cmp_ge_u32 s40, s35
	s_cbranch_scc1 .Lpzb_filled
	s_lshl_b32 s40, s40, 10
	v_add_u32_e32 v4, s40, v1
	ds_write_b128 v4, v[96:99]
	s_add_i32 s40, s34, 16
	s_cmp_ge_u32 s40, s35
	s_cbranch_scc1 .Lpzb_filled
	s_lshl_b32 s40, s40, 10
	v_add_u32_e32 v4, s40, v1
	ds_write_b128 v4, v[100:103]
	s_add_i32 s40, s34, 24
	s_cmp_ge_u32 s40, s35
	s_cbranch_scc1 .Lpzb_filled
	s_lshl_b32 s40, s40, 10
	v_add_u32_e32 v4, s40, v1
	ds_write_b128 v4, v[104:107]
	s_add_i32 s40, s34, 32
	s_cmp_ge_u32 s40, s35
	s_cbranch_scc1 .Lpzb_filled
	s_lshl_b32 s40, s40, 10
	v_add_u32_e32 v4, s40, v1
	ds_write_b128 v4, v[108:111]
	s_add_i32 s40, s34, 40
	s_cmp_ge_u32 s40, s35
	s_cbranch_scc1 .Lpzb_filled
	s_lshl_b32 s40, s40, 10
	v_add_u32_e32 v4, s40, v1
	ds_write_b128 v4, v[112:115]
	s_add_i32 s40, s34, 48
	s_cmp_ge_u32 s40, s35
	s_cbranch_scc1 .Lpzb_filled
	s_lshl_b32 s40, s40, 10
	v_add_u32_e32 v4, s40, v1
	ds_write_b128 v4, v[116:119]
	s_add_i32 s40, s34, 56
	s_cmp_ge_u32 s40, s35
	s_cbranch_scc1 .Lpzb_filled
	s_lshl_b32 s40, s40, 10
	v_add_u32_e32 v4, s40, v1
	ds_write_b128 v4, v[120:123]
	s_add_i32 s40, s34, 64
	s_cmp_ge_u32 s40, s35
	s_cbranch_scc1 .Lpzb_filled
	s_lshl_b32 s40, s40, 10
	v_add_u32_e32 v4, s40, v1
	ds_write_b128 v4, v[124:127]
	s_add_i32 s40, s34, 72
	s_cmp_ge_u32 s40, s35
	s_cbranch_scc1 .Lpzb_filled
	s_lshl_b32 s40, s40, 10
	v_add_u32_e32 v4, s40, v1
	ds_write_b128 v4, v[128:131]
.Lpzb_filled:
	s_lshl_b32 s41, s34, 3
	s_add_i32 s41, s41, s31
	s_sub_i32 s41, s41, s27
	v_add_u32_e32 v3, s41, v0
	v_cmp_le_i32_e64 s[36:37], 0, v3
	v_cmp_gt_i32_e64 s[12:13], s30, v3
	s_and_b64 s[36:37], s[36:37], s[12:13]
	v_cndmask_b32_e64 v5, 0, v14, s[36:37]
	s_lshl_b32 s41, s34, 3
	s_add_i32 s41, s41, 4
	s_add_i32 s41, s41, s31
	s_sub_i32 s41, s41, s27
	v_add_u32_e32 v3, s41, v0
	v_cmp_le_i32_e64 s[36:37], 0, v3
	v_cmp_gt_i32_e64 s[12:13], s30, v3
	s_and_b64 s[36:37], s[36:37], s[12:13]
	v_cndmask_b32_e64 v6, 0, v15, s[36:37]
	v_mov_b32_e32 v7, v16
	v_mov_b32_e32 v8, v17
	v_mov_b32_e32 v10, v18
	v_mov_b32_e32 v11, v19
	v_mov_b32_e32 v12, v20
	v_mov_b32_e32 v13, v21
	s_mov_b32 s25, s26
	s_waitcnt lgkmcnt(0)
	s_barrier
	s_add_i32 s24, s24, 0x100
	s_cmp_lt_u32 s24, 0x300
	s_cbranch_scc0 .Lpz_norq
	s_and_b32 s26, s24, 3
	s_lshr_b32 s28, s24, 2
	s_lshl_b32 s28, s28, 6
	s_lshl_b32 s27, 1, s26
	s_lshl_b32 s35, s27, 1
	s_add_i32 s35, s35, 64
	s_cmp_lt_u32 s28, 0x1000
	s_cbranch_scc0 .Lpzc_lat
	s_and_b32 s29, s28, 0xffffff00
	s_movk_i32 s30, 0x100
	s_mov_b32 s45, 30
	s_branch .Lpzc_seq

.Lpz_norq:
	s_cmp_eq_u32 s25, 0
	s_cbranch_scc1 .Lpz_c0
	s_cmp_eq_u32 s25, 1
	s_cbranch_scc1 .Lpz_c1
	s_cmp_eq_u32 s25, 2
	s_cbranch_scc1 .Lpz_c2
.Lpz_c3:
	s_lshl_b32 s40, s34, 3
	s_lshl_b32 s41, s40, 10
	v_add_u32_e32 v4, s41, v1
	ds_read_b128 v[40:43], v4
	ds_read_b128 v[44:47], v4 offset:1024
	ds_read_b128 v[48:51], v4 offset:2048
	ds_read_b128 v[52:55], v4 offset:8192
	ds_read_b128 v[56:59], v4 offset:9216
	ds_read_b128 v[60:63], v4 offset:10240
	ds_read_b128 v[64:67], v4 offset:11264
	ds_read_b128 v[68:71], v4 offset:16384
	ds_read_b128 v[72:75], v4 offset:17408
	ds_read_b128 v[76:79], v4 offset:18432
	s_waitcnt lgkmcnt(0)
	v_readlane_b32 s36, v5, 0
	v_pk_fma_f32 v[22:23], s[36:37], v[40:41], 0 op_sel_hi:[0,1,0]
	v_pk_fma_f32 v[24:25], s[36:37], v[42:43], 0 op_sel_hi:[0,1,0]
	v_readlane_b32 s12, v5, 1
	v_pk_fma_f32 v[22:23], s[12:13], v[44:45], v[22:23] op_sel_hi:[0,1,1]
	v_pk_fma_f32 v[24:25], s[12:13], v[46:47], v[24:25] op_sel_hi:[0,1,1]
	v_readlane_b32 s36, v5, 2
	v_pk_fma_f32 v[22:23], s[36:37], v[48:49], v[22:23] op_sel_hi:[0,1,1]
	v_pk_fma_f32 v[24:25], s[36:37], v[50:51], v[24:25] op_sel_hi:[0,1,1]
	ds_read_b128 v[80:83], v4 offset:3072
	ds_read_b128 v[84:87], v4 offset:4096
	ds_read_b128 v[88:91], v4 offset:5120
	s_waitcnt lgkmcnt(0)
	v_readlane_b32 s12, v5, 3
	v_pk_fma_f32 v[22:23], s[12:13], v[80:81], v[22:23] op_sel_hi:[0,1,1]
	v_pk_fma_f32 v[24:25], s[12:13], v[82:83], v[24:25] op_sel_hi:[0,1,1]
	v_readlane_b32 s36, v5, 4
	v_pk_fma_f32 v[22:23], s[36:37], v[84:85], v[22:23] op_sel_hi:[0,1,1]
	v_pk_fma_f32 v[24:25], s[36:37], v[86:87], v[24:25] op_sel_hi:[0,1,1]
	v_readlane_b32 s12, v5, 5
	v_pk_fma_f32 v[22:23], s[12:13], v[88:89], v[22:23] op_sel_hi:[0,1,1]
	v_pk_fma_f32 v[24:25], s[12:13], v[90:91], v[24:25] op_sel_hi:[0,1,1]
	ds_read_b128 v[80:83], v4 offset:6144
	ds_read_b128 v[84:87], v4 offset:7168
	s_waitcnt lgkmcnt(0)
	v_readlane_b32 s36, v5, 6
	v_pk_fma_f32 v[22:23], s[36:37], v[80:81], v[22:23] op_sel_hi:[0,1,1]
	v_pk_fma_f32 v[24:25], s[36:37], v[82:83], v[24:25] op_sel_hi:[0,1,1]
	v_readlane_b32 s12, v5, 7
	v_pk_fma_f32 v[22:23], s[12:13], v[84:85], v[22:23] op_sel_hi:[0,1,1]
	v_pk_fma_f32 v[24:25], s[12:13], v[86:87], v[24:25] op_sel_hi:[0,1,1]
	v_readlane_b32 s36, v5, 8
	v_pk_fma_f32 v[22:23], s[36:37], v[52:53], v[22:23] op_sel_hi:[0,1,1]
	v_pk_fma_f32 v[24:25], s[36:37], v[54:55], v[24:25] op_sel_hi:[0,1,1]
	v_readlane_b32 s12, v5, 9
	v_pk_fma_f32 v[22:23], s[12:13], v[56:57], v[22:23] op_sel_hi:[0,1,1]
	v_pk_fma_f32 v[24:25], s[12:13], v[58:59], v[24:25] op_sel_hi:[0,1,1]
	v_readlane_b32 s36, v5, 10
	v_pk_fma_f32 v[22:23], s[36:37], v[60:61], v[22:23] op_sel_hi:[0,1,1]
	v_pk_fma_f32 v[24:25], s[36:37], v[62:63], v[24:25] op_sel_hi:[0,1,1]
	v_readlane_b32 s12, v5, 11
	v_pk_fma_f32 v[22:23], s[12:13], v[64:65], v[22:23] op_sel_hi:[0,1,1]
	v_pk_fma_f32 v[24:25], s[12:13], v[66:67], v[24:25] op_sel_hi:[0,1,1]
	ds_read_b128 v[80:83], v4 offset:12288
	ds_read_b128 v[84:87], v4 offset:13312
	ds_read_b128 v[88:91], v4 offset:14336
	s_waitcnt lgkmcnt(0)
	v_readlane_b32 s36, v5, 12
	v_pk_fma_f32 v[22:23], s[36:37], v[80:81], v[22:23] op_sel_hi:[0,1,1]
	v_pk_fma_f32 v[24:25], s[36:37], v[82:83], v[24:25] op_sel_hi:[0,1,1]
	v_readlane_b32 s12, v5, 13
	v_pk_fma_f32 v[22:23], s[12:13], v[84:85], v[22:23] op_sel_hi:[0,1,1]
	v_pk_fma_f32 v[24:25], s[12:13], v[86:87], v[24:25] op_sel_hi:[0,1,1]
	v_readlane_b32 s36, v5, 14
	v_pk_fma_f32 v[22:23], s[36:37], v[88:89], v[22:23] op_sel_hi:[0,1,1]
	v_pk_fma_f32 v[24:25], s[36:37], v[90:91], v[24:25] op_sel_hi:[0,1,1]
	ds_read_b128 v[80:83], v4 offset:15360
	s_waitcnt lgkmcnt(0)
	v_readlane_b32 s12, v5, 15
	v_pk_fma_f32 v[22:23], s[12:13], v[80:81], v[22:23] op_sel_hi:[0,1,1]
	v_pk_fma_f32 v[24:25], s[12:13], v[82:83], v[24:25] op_sel_hi:[0,1,1]
	s_add_i32 s47, s40, 0
	v_readlane_b32 s50, v8, s47
	v_readlane_b32 s36, v5, 8
	v_pk_mul_f32 v[26:27], s[36:37], v[52:53] op_sel_hi:[0,1]
	v_pk_mul_f32 v[28:29], s[36:37], v[54:55] op_sel_hi:[0,1]
	v_mov_b32_e32 v32, s50
	v_pk_fma_f32 v[26:27], v[32:33], v[22:23], v[26:27] op_sel_hi:[0,1,1] neg_lo:[0,0,1] neg_hi:[0,0,1]
	v_pk_fma_f32 v[28:29], v[32:33], v[24:25], v[28:29] op_sel_hi:[0,1,1] neg_lo:[0,0,1] neg_hi:[0,0,1]
	v_pk_mul_f32 v[26:27], v[10:11], v[26:27]
	v_pk_mul_f32 v[28:29], v[12:13], v[28:29]
	v_cvt_pk_bf16_f32 v30, v26, v27
	v_cvt_pk_bf16_f32 v31, v28, v29
	s_lshl_b32 s47, s47, 11
	v_add_u32_e32 v9, s47, v7
	global_store_dwordx2 v9, v[30:31], s[22:23]
	v_readlane_b32 s36, v5, 0
	v_readlane_b32 s12, v5, 16
	v_pk_mul_f32 v[26:27], s[36:37], v[40:41] op_sel_hi:[0,1]
	v_pk_mul_f32 v[28:29], s[36:37], v[42:43] op_sel_hi:[0,1]
	v_pk_fma_f32 v[26:27], s[12:13], v[68:69], v[26:27] op_sel_hi:[0,1,1] neg_lo:[0,0,1] neg_hi:[0,0,1]
	v_pk_fma_f32 v[28:29], s[12:13], v[70:71], v[28:29] op_sel_hi:[0,1,1] neg_lo:[0,0,1] neg_hi:[0,0,1]
	v_pk_add_f32 v[22:23], v[22:23], v[26:27]
	v_pk_add_f32 v[24:25], v[24:25], v[28:29]
	s_add_i32 s47, s40, 1
	v_readlane_b32 s50, v8, s47
	v_readlane_b32 s36, v5, 9
	v_pk_mul_f32 v[26:27], s[36:37], v[56:57] op_sel_hi:[0,1]
	v_pk_mul_f32 v[28:29], s[36:37], v[58:59] op_sel_hi:[0,1]
	v_mov_b32_e32 v32, s50
	v_pk_fma_f32 v[26:27], v[32:33], v[22:23], v[26:27] op_sel_hi:[0,1,1] neg_lo:[0,0,1] neg_hi:[0,0,1]
	v_pk_fma_f32 v[28:29], v[32:33], v[24:25], v[28:29] op_sel_hi:[0,1,1] neg_lo:[0,0,1] neg_hi:[0,0,1]
	v_pk_mul_f32 v[26:27], v[10:11], v[26:27]
	v_pk_mul_f32 v[28:29], v[12:13], v[28:29]
	v_cvt_pk_bf16_f32 v30, v26, v27
	v_cvt_pk_bf16_f32 v31, v28, v29
	s_lshl_b32 s47, s47, 11
	v_add_u32_e32 v9, s47, v7
	global_store_dwordx2 v9, v[30:31], s[22:23]
	v_readlane_b32 s36, v5, 1
	v_readlane_b32 s12, v5, 17
	v_pk_mul_f32 v[26:27], s[36:37], v[44:45] op_sel_hi:[0,1]
	v_pk_mul_f32 v[28:29], s[36:37], v[46:47] op_sel_hi:[0,1]
	v_pk_fma_f32 v[26:27], s[12:13], v[72:73], v[26:27] op_sel_hi:[0,1,1] neg_lo:[0,0,1] neg_hi:[0,0,1]
	v_pk_fma_f32 v[28:29], s[12:13], v[74:75], v[28:29] op_sel_hi:[0,1,1] neg_lo:[0,0,1] neg_hi:[0,0,1]
	v_pk_add_f32 v[22:23], v[22:23], v[26:27]
	v_pk_add_f32 v[24:25], v[24:25], v[28:29]
	s_add_i32 s47, s40, 2
	v_readlane_b32 s50, v8, s47
	v_readlane_b32 s36, v5, 10
	v_pk_mul_f32 v[26:27], s[36:37], v[60:61] op_sel_hi:[0,1]
	v_pk_mul_f32 v[28:29], s[36:37], v[62:63] op_sel_hi:[0,1]
	v_mov_b32_e32 v32, s50
	v_pk_fma_f32 v[26:27], v[32:33], v[22:23], v[26:27] op_sel_hi:[0,1,1] neg_lo:[0,0,1] neg_hi:[0,0,1]
	v_pk_fma_f32 v[28:29], v[32:33], v[24:25], v[28:29] op_sel_hi:[0,1,1] neg_lo:[0,0,1] neg_hi:[0,0,1]
	v_pk_mul_f32 v[26:27], v[10:11], v[26:27]
	v_pk_mul_f32 v[28:29], v[12:13], v[28:29]
	v_cvt_pk_bf16_f32 v30, v26, v27
	v_cvt_pk_bf16_f32 v31, v28, v29
	s_lshl_b32 s47, s47, 11
	v_add_u32_e32 v9, s47, v7
	global_store_dwordx2 v9, v[30:31], s[22:23]
	v_readlane_b32 s36, v5, 2
	v_readlane_b32 s12, v5, 18
	v_pk_mul_f32 v[26:27], s[36:37], v[48:49] op_sel_hi:[0,1]
	v_pk_mul_f32 v[28:29], s[36:37], v[50:51] op_sel_hi:[0,1]
	v_pk_fma_f32 v[26:27], s[12:13], v[76:77], v[26:27] op_sel_hi:[0,1,1] neg_lo:[0,0,1] neg_hi:[0,0,1]
	v_pk_fma_f32 v[28:29], s[12:13], v[78:79], v[28:29] op_sel_hi:[0,1,1] neg_lo:[0,0,1] neg_hi:[0,0,1]
	v_pk_add_f32 v[22:23], v[22:23], v[26:27]
	v_pk_add_f32 v[24:25], v[24:25], v[28:29]
	s_add_i32 s47, s40, 3
	v_readlane_b32 s50, v8, s47
	v_readlane_b32 s36, v5, 11
	v_pk_mul_f32 v[26:27], s[36:37], v[64:65] op_sel_hi:[0,1]
	v_pk_mul_f32 v[28:29], s[36:37], v[66:67] op_sel_hi:[0,1]
	v_mov_b32_e32 v32, s50
	v_pk_fma_f32 v[26:27], v[32:33], v[22:23], v[26:27] op_sel_hi:[0,1,1] neg_lo:[0,0,1] neg_hi:[0,0,1]
	v_pk_fma_f32 v[28:29], v[32:33], v[24:25], v[28:29] op_sel_hi:[0,1,1] neg_lo:[0,0,1] neg_hi:[0,0,1]
	v_pk_mul_f32 v[26:27], v[10:11], v[26:27]
	v_pk_mul_f32 v[28:29], v[12:13], v[28:29]
	v_cvt_pk_bf16_f32 v30, v26, v27
	v_cvt_pk_bf16_f32 v31, v28, v29
	s_lshl_b32 s47, s47, 11
	v_add_u32_e32 v9, s47, v7
	global_store_dwordx2 v9, v[30:31], s[22:23]
	s_lshl_b32 s40, s34, 3
	s_add_i32 s40, s40, 4
	s_lshl_b32 s41, s40, 10
	v_add_u32_e32 v4, s41, v1
	ds_read_b128 v[40:43], v4
	ds_read_b128 v[44:47], v4 offset:1024
	ds_read_b128 v[48:51], v4 offset:2048
	ds_read_b128 v[52:55], v4 offset:8192
	ds_read_b128 v[56:59], v4 offset:9216
	ds_read_b128 v[60:63], v4 offset:10240
	ds_read_b128 v[64:67], v4 offset:11264
	ds_read_b128 v[68:71], v4 offset:16384
	ds_read_b128 v[72:75], v4 offset:17408
	ds_read_b128 v[76:79], v4 offset:18432
	s_waitcnt lgkmcnt(0)
	v_readlane_b32 s36, v6, 0
	v_pk_fma_f32 v[22:23], s[36:37], v[40:41], 0 op_sel_hi:[0,1,0]
	v_pk_fma_f32 v[24:25], s[36:37], v[42:43], 0 op_sel_hi:[0,1,0]
	v_readlane_b32 s12, v6, 1
	v_pk_fma_f32 v[22:23], s[12:13], v[44:45], v[22:23] op_sel_hi:[0,1,1]
	v_pk_fma_f32 v[24:25], s[12:13], v[46:47], v[24:25] op_sel_hi:[0,1,1]
	v_readlane_b32 s36, v6, 2
	v_pk_fma_f32 v[22:23], s[36:37], v[48:49], v[22:23] op_sel_hi:[0,1,1]
	v_pk_fma_f32 v[24:25], s[36:37], v[50:51], v[24:25] op_sel_hi:[0,1,1]
	ds_read_b128 v[80:83], v4 offset:3072
	ds_read_b128 v[84:87], v4 offset:4096
	ds_read_b128 v[88:91], v4 offset:5120
	s_waitcnt lgkmcnt(0)
	v_readlane_b32 s12, v6, 3
	v_pk_fma_f32 v[22:23], s[12:13], v[80:81], v[22:23] op_sel_hi:[0,1,1]
	v_pk_fma_f32 v[24:25], s[12:13], v[82:83], v[24:25] op_sel_hi:[0,1,1]
	v_readlane_b32 s36, v6, 4
	v_pk_fma_f32 v[22:23], s[36:37], v[84:85], v[22:23] op_sel_hi:[0,1,1]
	v_pk_fma_f32 v[24:25], s[36:37], v[86:87], v[24:25] op_sel_hi:[0,1,1]
	v_readlane_b32 s12, v6, 5
	v_pk_fma_f32 v[22:23], s[12:13], v[88:89], v[22:23] op_sel_hi:[0,1,1]
	v_pk_fma_f32 v[24:25], s[12:13], v[90:91], v[24:25] op_sel_hi:[0,1,1]
	ds_read_b128 v[80:83], v4 offset:6144
	ds_read_b128 v[84:87], v4 offset:7168
	s_waitcnt lgkmcnt(0)
	v_readlane_b32 s36, v6, 6
	v_pk_fma_f32 v[22:23], s[36:37], v[80:81], v[22:23] op_sel_hi:[0,1,1]
	v_pk_fma_f32 v[24:25], s[36:37], v[82:83], v[24:25] op_sel_hi:[0,1,1]
	v_readlane_b32 s12, v6, 7
	v_pk_fma_f32 v[22:23], s[12:13], v[84:85], v[22:23] op_sel_hi:[0,1,1]
	v_pk_fma_f32 v[24:25], s[12:13], v[86:87], v[24:25] op_sel_hi:[0,1,1]
	v_readlane_b32 s36, v6, 8
	v_pk_fma_f32 v[22:23], s[36:37], v[52:53], v[22:23] op_sel_hi:[0,1,1]
	v_pk_fma_f32 v[24:25], s[36:37], v[54:55], v[24:25] op_sel_hi:[0,1,1]
	v_readlane_b32 s12, v6, 9
	v_pk_fma_f32 v[22:23], s[12:13], v[56:57], v[22:23] op_sel_hi:[0,1,1]
	v_pk_fma_f32 v[24:25], s[12:13], v[58:59], v[24:25] op_sel_hi:[0,1,1]
	v_readlane_b32 s36, v6, 10
	v_pk_fma_f32 v[22:23], s[36:37], v[60:61], v[22:23] op_sel_hi:[0,1,1]
	v_pk_fma_f32 v[24:25], s[36:37], v[62:63], v[24:25] op_sel_hi:[0,1,1]
	v_readlane_b32 s12, v6, 11
	v_pk_fma_f32 v[22:23], s[12:13], v[64:65], v[22:23] op_sel_hi:[0,1,1]
	v_pk_fma_f32 v[24:25], s[12:13], v[66:67], v[24:25] op_sel_hi:[0,1,1]
	ds_read_b128 v[80:83], v4 offset:12288
	ds_read_b128 v[84:87], v4 offset:13312
	ds_read_b128 v[88:91], v4 offset:14336
	s_waitcnt lgkmcnt(0)
	v_readlane_b32 s36, v6, 12
	v_pk_fma_f32 v[22:23], s[36:37], v[80:81], v[22:23] op_sel_hi:[0,1,1]
	v_pk_fma_f32 v[24:25], s[36:37], v[82:83], v[24:25] op_sel_hi:[0,1,1]
	v_readlane_b32 s12, v6, 13
	v_pk_fma_f32 v[22:23], s[12:13], v[84:85], v[22:23] op_sel_hi:[0,1,1]
	v_pk_fma_f32 v[24:25], s[12:13], v[86:87], v[24:25] op_sel_hi:[0,1,1]
	v_readlane_b32 s36, v6, 14
	v_pk_fma_f32 v[22:23], s[36:37], v[88:89], v[22:23] op_sel_hi:[0,1,1]
	v_pk_fma_f32 v[24:25], s[36:37], v[90:91], v[24:25] op_sel_hi:[0,1,1]
	ds_read_b128 v[80:83], v4 offset:15360
	s_waitcnt lgkmcnt(0)
	v_readlane_b32 s12, v6, 15
	v_pk_fma_f32 v[22:23], s[12:13], v[80:81], v[22:23] op_sel_hi:[0,1,1]
	v_pk_fma_f32 v[24:25], s[12:13], v[82:83], v[24:25] op_sel_hi:[0,1,1]
	s_add_i32 s47, s40, 0
	v_readlane_b32 s50, v8, s47
	v_readlane_b32 s36, v6, 8
	v_pk_mul_f32 v[26:27], s[36:37], v[52:53] op_sel_hi:[0,1]
	v_pk_mul_f32 v[28:29], s[36:37], v[54:55] op_sel_hi:[0,1]
	v_mov_b32_e32 v32, s50
	v_pk_fma_f32 v[26:27], v[32:33], v[22:23], v[26:27] op_sel_hi:[0,1,1] neg_lo:[0,0,1] neg_hi:[0,0,1]
	v_pk_fma_f32 v[28:29], v[32:33], v[24:25], v[28:29] op_sel_hi:[0,1,1] neg_lo:[0,0,1] neg_hi:[0,0,1]
	v_pk_mul_f32 v[26:27], v[10:11], v[26:27]
	v_pk_mul_f32 v[28:29], v[12:13], v[28:29]
	v_cvt_pk_bf16_f32 v30, v26, v27
	v_cvt_pk_bf16_f32 v31, v28, v29
	s_lshl_b32 s47, s47, 11
	v_add_u32_e32 v9, s47, v7
	global_store_dwordx2 v9, v[30:31], s[22:23]
	v_readlane_b32 s36, v6, 0
	v_readlane_b32 s12, v6, 16
	v_pk_mul_f32 v[26:27], s[36:37], v[40:41] op_sel_hi:[0,1]
	v_pk_mul_f32 v[28:29], s[36:37], v[42:43] op_sel_hi:[0,1]
	v_pk_fma_f32 v[26:27], s[12:13], v[68:69], v[26:27] op_sel_hi:[0,1,1] neg_lo:[0,0,1] neg_hi:[0,0,1]
	v_pk_fma_f32 v[28:29], s[12:13], v[70:71], v[28:29] op_sel_hi:[0,1,1] neg_lo:[0,0,1] neg_hi:[0,0,1]
	v_pk_add_f32 v[22:23], v[22:23], v[26:27]
	v_pk_add_f32 v[24:25], v[24:25], v[28:29]
	s_add_i32 s47, s40, 1
	v_readlane_b32 s50, v8, s47
	v_readlane_b32 s36, v6, 9
	v_pk_mul_f32 v[26:27], s[36:37], v[56:57] op_sel_hi:[0,1]
	v_pk_mul_f32 v[28:29], s[36:37], v[58:59] op_sel_hi:[0,1]
	v_mov_b32_e32 v32, s50
	v_pk_fma_f32 v[26:27], v[32:33], v[22:23], v[26:27] op_sel_hi:[0,1,1] neg_lo:[0,0,1] neg_hi:[0,0,1]
	v_pk_fma_f32 v[28:29], v[32:33], v[24:25], v[28:29] op_sel_hi:[0,1,1] neg_lo:[0,0,1] neg_hi:[0,0,1]
	v_pk_mul_f32 v[26:27], v[10:11], v[26:27]
	v_pk_mul_f32 v[28:29], v[12:13], v[28:29]
	v_cvt_pk_bf16_f32 v30, v26, v27
	v_cvt_pk_bf16_f32 v31, v28, v29
	s_lshl_b32 s47, s47, 11
	v_add_u32_e32 v9, s47, v7
	global_store_dwordx2 v9, v[30:31], s[22:23]
	v_readlane_b32 s36, v6, 1
	v_readlane_b32 s12, v6, 17
	v_pk_mul_f32 v[26:27], s[36:37], v[44:45] op_sel_hi:[0,1]
	v_pk_mul_f32 v[28:29], s[36:37], v[46:47] op_sel_hi:[0,1]
	v_pk_fma_f32 v[26:27], s[12:13], v[72:73], v[26:27] op_sel_hi:[0,1,1] neg_lo:[0,0,1] neg_hi:[0,0,1]
	v_pk_fma_f32 v[28:29], s[12:13], v[74:75], v[28:29] op_sel_hi:[0,1,1] neg_lo:[0,0,1] neg_hi:[0,0,1]
	v_pk_add_f32 v[22:23], v[22:23], v[26:27]
	v_pk_add_f32 v[24:25], v[24:25], v[28:29]
	s_add_i32 s47, s40, 2
	v_readlane_b32 s50, v8, s47
	v_readlane_b32 s36, v6, 10
	v_pk_mul_f32 v[26:27], s[36:37], v[60:61] op_sel_hi:[0,1]
	v_pk_mul_f32 v[28:29], s[36:37], v[62:63] op_sel_hi:[0,1]
	v_mov_b32_e32 v32, s50
	v_pk_fma_f32 v[26:27], v[32:33], v[22:23], v[26:27] op_sel_hi:[0,1,1] neg_lo:[0,0,1] neg_hi:[0,0,1]
	v_pk_fma_f32 v[28:29], v[32:33], v[24:25], v[28:29] op_sel_hi:[0,1,1] neg_lo:[0,0,1] neg_hi:[0,0,1]
	v_pk_mul_f32 v[26:27], v[10:11], v[26:27]
	v_pk_mul_f32 v[28:29], v[12:13], v[28:29]
	v_cvt_pk_bf16_f32 v30, v26, v27
	v_cvt_pk_bf16_f32 v31, v28, v29
	s_lshl_b32 s47, s47, 11
	v_add_u32_e32 v9, s47, v7
	global_store_dwordx2 v9, v[30:31], s[22:23]
	v_readlane_b32 s36, v6, 2
	v_readlane_b32 s12, v6, 18
	v_pk_mul_f32 v[26:27], s[36:37], v[48:49] op_sel_hi:[0,1]
	v_pk_mul_f32 v[28:29], s[36:37], v[50:51] op_sel_hi:[0,1]
	v_pk_fma_f32 v[26:27], s[12:13], v[76:77], v[26:27] op_sel_hi:[0,1,1] neg_lo:[0,0,1] neg_hi:[0,0,1]
	v_pk_fma_f32 v[28:29], s[12:13], v[78:79], v[28:29] op_sel_hi:[0,1,1] neg_lo:[0,0,1] neg_hi:[0,0,1]
	v_pk_add_f32 v[22:23], v[22:23], v[26:27]
	v_pk_add_f32 v[24:25], v[24:25], v[28:29]
	s_add_i32 s47, s40, 3
	v_readlane_b32 s50, v8, s47
	v_readlane_b32 s36, v6, 11
	v_pk_mul_f32 v[26:27], s[36:37], v[64:65] op_sel_hi:[0,1]
	v_pk_mul_f32 v[28:29], s[36:37], v[66:67] op_sel_hi:[0,1]
	v_mov_b32_e32 v32, s50
	v_pk_fma_f32 v[26:27], v[32:33], v[22:23], v[26:27] op_sel_hi:[0,1,1] neg_lo:[0,0,1] neg_hi:[0,0,1]
	v_pk_fma_f32 v[28:29], v[32:33], v[24:25], v[28:29] op_sel_hi:[0,1,1] neg_lo:[0,0,1] neg_hi:[0,0,1]
	v_pk_mul_f32 v[26:27], v[10:11], v[26:27]
	v_pk_mul_f32 v[28:29], v[12:13], v[28:29]
	v_cvt_pk_bf16_f32 v30, v26, v27
	v_cvt_pk_bf16_f32 v31, v28, v29
	s_lshl_b32 s47, s47, 11
	v_add_u32_e32 v9, s47, v7
	global_store_dwordx2 v9, v[30:31], s[22:23]
	s_branch .Lpz_next
.Lpz_c2:
	s_lshl_b32 s40, s34, 3
	s_lshl_b32 s41, s40, 10
	v_add_u32_e32 v4, s41, v1
	ds_read_b128 v[40:43], v4
	ds_read_b128 v[44:47], v4 offset:1024
	ds_read_b128 v[48:51], v4 offset:2048
	ds_read_b128 v[52:55], v4 offset:3072
	ds_read_b128 v[56:59], v4 offset:4096
	ds_read_b128 v[60:63], v4 offset:5120
	ds_read_b128 v[64:67], v4 offset:6144
	ds_read_b128 v[68:71], v4 offset:7168
	ds_read_b128 v[72:75], v4 offset:8192
	ds_read_b128 v[76:79], v4 offset:9216
	ds_read_b128 v[80:83], v4 offset:10240
	s_waitcnt lgkmcnt(0)
	v_readlane_b32 s36, v5, 0
	v_pk_fma_f32 v[22:23], s[36:37], v[40:41], 0 op_sel_hi:[0,1,0]
	v_pk_fma_f32 v[24:25], s[36:37], v[42:43], 0 op_sel_hi:[0,1,0]
	v_readlane_b32 s12, v5, 1
	v_pk_fma_f32 v[22:23], s[12:13], v[44:45], v[22:23] op_sel_hi:[0,1,1]
	v_pk_fma_f32 v[24:25], s[12:13], v[46:47], v[24:25] op_sel_hi:[0,1,1]
	v_readlane_b32 s36, v5, 2
	v_pk_fma_f32 v[22:23], s[36:37], v[48:49], v[22:23] op_sel_hi:[0,1,1]
	v_pk_fma_f32 v[24:25], s[36:37], v[50:51], v[24:25] op_sel_hi:[0,1,1]
	v_readlane_b32 s12, v5, 3
	v_pk_fma_f32 v[22:23], s[12:13], v[52:53], v[22:23] op_sel_hi:[0,1,1]
	v_pk_fma_f32 v[24:25], s[12:13], v[54:55], v[24:25] op_sel_hi:[0,1,1]
	v_readlane_b32 s36, v5, 4
	v_pk_fma_f32 v[22:23], s[36:37], v[56:57], v[22:23] op_sel_hi:[0,1,1]
	v_pk_fma_f32 v[24:25], s[36:37], v[58:59], v[24:25] op_sel_hi:[0,1,1]
	v_readlane_b32 s12, v5, 5
	v_pk_fma_f32 v[22:23], s[12:13], v[60:61], v[22:23] op_sel_hi:[0,1,1]
	v_pk_fma_f32 v[24:25], s[12:13], v[62:63], v[24:25] op_sel_hi:[0,1,1]
	v_readlane_b32 s36, v5, 6
	v_pk_fma_f32 v[22:23], s[36:37], v[64:65], v[22:23] op_sel_hi:[0,1,1]
	v_pk_fma_f32 v[24:25], s[36:37], v[66:67], v[24:25] op_sel_hi:[0,1,1]
	v_readlane_b32 s12, v5, 7
	v_pk_fma_f32 v[22:23], s[12:13], v[68:69], v[22:23] op_sel_hi:[0,1,1]
	v_pk_fma_f32 v[24:25], s[12:13], v[70:71], v[24:25] op_sel_hi:[0,1,1]
	s_add_i32 s47, s40, 0
	v_readlane_b32 s50, v8, s47
	v_readlane_b32 s36, v5, 4
	v_pk_mul_f32 v[26:27], s[36:37], v[56:57] op_sel_hi:[0,1]
	v_pk_mul_f32 v[28:29], s[36:37], v[58:59] op_sel_hi:[0,1]
	v_mov_b32_e32 v32, s50
	v_pk_fma_f32 v[26:27], v[32:33], v[22:23], v[26:27] op_sel_hi:[0,1,1] neg_lo:[0,0,1] neg_hi:[0,0,1]
	v_pk_fma_f32 v[28:29], v[32:33], v[24:25], v[28:29] op_sel_hi:[0,1,1] neg_lo:[0,0,1] neg_hi:[0,0,1]
	v_pk_mul_f32 v[26:27], v[10:11], v[26:27]
	v_pk_mul_f32 v[28:29], v[12:13], v[28:29]
	v_cvt_pk_bf16_f32 v30, v26, v27
	v_cvt_pk_bf16_f32 v31, v28, v29
	s_lshl_b32 s47, s47, 11
	v_add_u32_e32 v9, s47, v7
	global_store_dwordx2 v9, v[30:31], s[22:23]
	v_readlane_b32 s36, v5, 0
	v_readlane_b32 s12, v5, 8
	v_pk_mul_f32 v[26:27], s[36:37], v[40:41] op_sel_hi:[0,1]
	v_pk_mul_f32 v[28:29], s[36:37], v[42:43] op_sel_hi:[0,1]
	v_pk_fma_f32 v[26:27], s[12:13], v[72:73], v[26:27] op_sel_hi:[0,1,1] neg_lo:[0,0,1] neg_hi:[0,0,1]
	v_pk_fma_f32 v[28:29], s[12:13], v[74:75], v[28:29] op_sel_hi:[0,1,1] neg_lo:[0,0,1] neg_hi:[0,0,1]
	v_pk_add_f32 v[22:23], v[22:23], v[26:27]
	v_pk_add_f32 v[24:25], v[24:25], v[28:29]
	s_add_i32 s47, s40, 1
	v_readlane_b32 s50, v8, s47
	v_readlane_b32 s36, v5, 5
	v_pk_mul_f32 v[26:27], s[36:37], v[60:61] op_sel_hi:[0,1]
	v_pk_mul_f32 v[28:29], s[36:37], v[62:63] op_sel_hi:[0,1]
	v_mov_b32_e32 v32, s50
	v_pk_fma_f32 v[26:27], v[32:33], v[22:23], v[26:27] op_sel_hi:[0,1,1] neg_lo:[0,0,1] neg_hi:[0,0,1]
	v_pk_fma_f32 v[28:29], v[32:33], v[24:25], v[28:29] op_sel_hi:[0,1,1] neg_lo:[0,0,1] neg_hi:[0,0,1]
	v_pk_mul_f32 v[26:27], v[10:11], v[26:27]
	v_pk_mul_f32 v[28:29], v[12:13], v[28:29]
	v_cvt_pk_bf16_f32 v30, v26, v27
	v_cvt_pk_bf16_f32 v31, v28, v29
	s_lshl_b32 s47, s47, 11
	v_add_u32_e32 v9, s47, v7
	global_store_dwordx2 v9, v[30:31], s[22:23]
	v_readlane_b32 s36, v5, 1
	v_readlane_b32 s12, v5, 9
	v_pk_mul_f32 v[26:27], s[36:37], v[44:45] op_sel_hi:[0,1]
	v_pk_mul_f32 v[28:29], s[36:37], v[46:47] op_sel_hi:[0,1]
	v_pk_fma_f32 v[26:27], s[12:13], v[76:77], v[26:27] op_sel_hi:[0,1,1] neg_lo:[0,0,1] neg_hi:[0,0,1]
	v_pk_fma_f32 v[28:29], s[12:13], v[78:79], v[28:29] op_sel_hi:[0,1,1] neg_lo:[0,0,1] neg_hi:[0,0,1]
	v_pk_add_f32 v[22:23], v[22:23], v[26:27]
	v_pk_add_f32 v[24:25], v[24:25], v[28:29]
	s_add_i32 s47, s40, 2
	v_readlane_b32 s50, v8, s47
	v_readlane_b32 s36, v5, 6
	v_pk_mul_f32 v[26:27], s[36:37], v[64:65] op_sel_hi:[0,1]
	v_pk_mul_f32 v[28:29], s[36:37], v[66:67] op_sel_hi:[0,1]
	v_mov_b32_e32 v32, s50
	v_pk_fma_f32 v[26:27], v[32:33], v[22:23], v[26:27] op_sel_hi:[0,1,1] neg_lo:[0,0,1] neg_hi:[0,0,1]
	v_pk_fma_f32 v[28:29], v[32:33], v[24:25], v[28:29] op_sel_hi:[0,1,1] neg_lo:[0,0,1] neg_hi:[0,0,1]
	v_pk_mul_f32 v[26:27], v[10:11], v[26:27]
	v_pk_mul_f32 v[28:29], v[12:13], v[28:29]
	v_cvt_pk_bf16_f32 v30, v26, v27
	v_cvt_pk_bf16_f32 v31, v28, v29
	s_lshl_b32 s47, s47, 11
	v_add_u32_e32 v9, s47, v7
	global_store_dwordx2 v9, v[30:31], s[22:23]
	v_readlane_b32 s36, v5, 2
	v_readlane_b32 s12, v5, 10
	v_pk_mul_f32 v[26:27], s[36:37], v[48:49] op_sel_hi:[0,1]
	v_pk_mul_f32 v[28:29], s[36:37], v[50:51] op_sel_hi:[0,1]
	v_pk_fma_f32 v[26:27], s[12:13], v[80:81], v[26:27] op_sel_hi:[0,1,1] neg_lo:[0,0,1] neg_hi:[0,0,1]
	v_pk_fma_f32 v[28:29], s[12:13], v[82:83], v[28:29] op_sel_hi:[0,1,1] neg_lo:[0,0,1] neg_hi:[0,0,1]
	v_pk_add_f32 v[22:23], v[22:23], v[26:27]
	v_pk_add_f32 v[24:25], v[24:25], v[28:29]
	s_add_i32 s47, s40, 3
	v_readlane_b32 s50, v8, s47
	v_readlane_b32 s36, v5, 7
	v_pk_mul_f32 v[26:27], s[36:37], v[68:69] op_sel_hi:[0,1]
	v_pk_mul_f32 v[28:29], s[36:37], v[70:71] op_sel_hi:[0,1]
	v_mov_b32_e32 v32, s50
	v_pk_fma_f32 v[26:27], v[32:33], v[22:23], v[26:27] op_sel_hi:[0,1,1] neg_lo:[0,0,1] neg_hi:[0,0,1]
	v_pk_fma_f32 v[28:29], v[32:33], v[24:25], v[28:29] op_sel_hi:[0,1,1] neg_lo:[0,0,1] neg_hi:[0,0,1]
	v_pk_mul_f32 v[26:27], v[10:11], v[26:27]
	v_pk_mul_f32 v[28:29], v[12:13], v[28:29]
	v_cvt_pk_bf16_f32 v30, v26, v27
	v_cvt_pk_bf16_f32 v31, v28, v29
	s_lshl_b32 s47, s47, 11
	v_add_u32_e32 v9, s47, v7
	global_store_dwordx2 v9, v[30:31], s[22:23]
	s_lshl_b32 s40, s34, 3
	s_add_i32 s40, s40, 4
	s_lshl_b32 s41, s40, 10
	v_add_u32_e32 v4, s41, v1
	ds_read_b128 v[40:43], v4
	ds_read_b128 v[44:47], v4 offset:1024
	ds_read_b128 v[48:51], v4 offset:2048
	ds_read_b128 v[52:55], v4 offset:3072
	ds_read_b128 v[56:59], v4 offset:4096
	ds_read_b128 v[60:63], v4 offset:5120
	ds_read_b128 v[64:67], v4 offset:6144
	ds_read_b128 v[68:71], v4 offset:7168
	ds_read_b128 v[72:75], v4 offset:8192
	ds_read_b128 v[76:79], v4 offset:9216
	ds_read_b128 v[80:83], v4 offset:10240
	s_waitcnt lgkmcnt(0)
	v_readlane_b32 s36, v6, 0
	v_pk_fma_f32 v[22:23], s[36:37], v[40:41], 0 op_sel_hi:[0,1,0]
	v_pk_fma_f32 v[24:25], s[36:37], v[42:43], 0 op_sel_hi:[0,1,0]
	v_readlane_b32 s12, v6, 1
	v_pk_fma_f32 v[22:23], s[12:13], v[44:45], v[22:23] op_sel_hi:[0,1,1]
	v_pk_fma_f32 v[24:25], s[12:13], v[46:47], v[24:25] op_sel_hi:[0,1,1]
	v_readlane_b32 s36, v6, 2
	v_pk_fma_f32 v[22:23], s[36:37], v[48:49], v[22:23] op_sel_hi:[0,1,1]
	v_pk_fma_f32 v[24:25], s[36:37], v[50:51], v[24:25] op_sel_hi:[0,1,1]
	v_readlane_b32 s12, v6, 3
	v_pk_fma_f32 v[22:23], s[12:13], v[52:53], v[22:23] op_sel_hi:[0,1,1]
	v_pk_fma_f32 v[24:25], s[12:13], v[54:55], v[24:25] op_sel_hi:[0,1,1]
	v_readlane_b32 s36, v6, 4
	v_pk_fma_f32 v[22:23], s[36:37], v[56:57], v[22:23] op_sel_hi:[0,1,1]
	v_pk_fma_f32 v[24:25], s[36:37], v[58:59], v[24:25] op_sel_hi:[0,1,1]
	v_readlane_b32 s12, v6, 5
	v_pk_fma_f32 v[22:23], s[12:13], v[60:61], v[22:23] op_sel_hi:[0,1,1]
	v_pk_fma_f32 v[24:25], s[12:13], v[62:63], v[24:25] op_sel_hi:[0,1,1]
	v_readlane_b32 s36, v6, 6
	v_pk_fma_f32 v[22:23], s[36:37], v[64:65], v[22:23] op_sel_hi:[0,1,1]
	v_pk_fma_f32 v[24:25], s[36:37], v[66:67], v[24:25] op_sel_hi:[0,1,1]
	v_readlane_b32 s12, v6, 7
	v_pk_fma_f32 v[22:23], s[12:13], v[68:69], v[22:23] op_sel_hi:[0,1,1]
	v_pk_fma_f32 v[24:25], s[12:13], v[70:71], v[24:25] op_sel_hi:[0,1,1]
	s_add_i32 s47, s40, 0
	v_readlane_b32 s50, v8, s47
	v_readlane_b32 s36, v6, 4
	v_pk_mul_f32 v[26:27], s[36:37], v[56:57] op_sel_hi:[0,1]
	v_pk_mul_f32 v[28:29], s[36:37], v[58:59] op_sel_hi:[0,1]
	v_mov_b32_e32 v32, s50
	v_pk_fma_f32 v[26:27], v[32:33], v[22:23], v[26:27] op_sel_hi:[0,1,1] neg_lo:[0,0,1] neg_hi:[0,0,1]
	v_pk_fma_f32 v[28:29], v[32:33], v[24:25], v[28:29] op_sel_hi:[0,1,1] neg_lo:[0,0,1] neg_hi:[0,0,1]
	v_pk_mul_f32 v[26:27], v[10:11], v[26:27]
	v_pk_mul_f32 v[28:29], v[12:13], v[28:29]
	v_cvt_pk_bf16_f32 v30, v26, v27
	v_cvt_pk_bf16_f32 v31, v28, v29
	s_lshl_b32 s47, s47, 11
	v_add_u32_e32 v9, s47, v7
	global_store_dwordx2 v9, v[30:31], s[22:23]
	v_readlane_b32 s36, v6, 0
	v_readlane_b32 s12, v6, 8
	v_pk_mul_f32 v[26:27], s[36:37], v[40:41] op_sel_hi:[0,1]
	v_pk_mul_f32 v[28:29], s[36:37], v[42:43] op_sel_hi:[0,1]
	v_pk_fma_f32 v[26:27], s[12:13], v[72:73], v[26:27] op_sel_hi:[0,1,1] neg_lo:[0,0,1] neg_hi:[0,0,1]
	v_pk_fma_f32 v[28:29], s[12:13], v[74:75], v[28:29] op_sel_hi:[0,1,1] neg_lo:[0,0,1] neg_hi:[0,0,1]
	v_pk_add_f32 v[22:23], v[22:23], v[26:27]
	v_pk_add_f32 v[24:25], v[24:25], v[28:29]
	s_add_i32 s47, s40, 1
	v_readlane_b32 s50, v8, s47
	v_readlane_b32 s36, v6, 5
	v_pk_mul_f32 v[26:27], s[36:37], v[60:61] op_sel_hi:[0,1]
	v_pk_mul_f32 v[28:29], s[36:37], v[62:63] op_sel_hi:[0,1]
	v_mov_b32_e32 v32, s50
	v_pk_fma_f32 v[26:27], v[32:33], v[22:23], v[26:27] op_sel_hi:[0,1,1] neg_lo:[0,0,1] neg_hi:[0,0,1]
	v_pk_fma_f32 v[28:29], v[32:33], v[24:25], v[28:29] op_sel_hi:[0,1,1] neg_lo:[0,0,1] neg_hi:[0,0,1]
	v_pk_mul_f32 v[26:27], v[10:11], v[26:27]
	v_pk_mul_f32 v[28:29], v[12:13], v[28:29]
	v_cvt_pk_bf16_f32 v30, v26, v27
	v_cvt_pk_bf16_f32 v31, v28, v29
	s_lshl_b32 s47, s47, 11
	v_add_u32_e32 v9, s47, v7
	global_store_dwordx2 v9, v[30:31], s[22:23]
	v_readlane_b32 s36, v6, 1
	v_readlane_b32 s12, v6, 9
	v_pk_mul_f32 v[26:27], s[36:37], v[44:45] op_sel_hi:[0,1]
	v_pk_mul_f32 v[28:29], s[36:37], v[46:47] op_sel_hi:[0,1]
	v_pk_fma_f32 v[26:27], s[12:13], v[76:77], v[26:27] op_sel_hi:[0,1,1] neg_lo:[0,0,1] neg_hi:[0,0,1]
	v_pk_fma_f32 v[28:29], s[12:13], v[78:79], v[28:29] op_sel_hi:[0,1,1] neg_lo:[0,0,1] neg_hi:[0,0,1]
	v_pk_add_f32 v[22:23], v[22:23], v[26:27]
	v_pk_add_f32 v[24:25], v[24:25], v[28:29]
	s_add_i32 s47, s40, 2
	v_readlane_b32 s50, v8, s47
	v_readlane_b32 s36, v6, 6
	v_pk_mul_f32 v[26:27], s[36:37], v[64:65] op_sel_hi:[0,1]
	v_pk_mul_f32 v[28:29], s[36:37], v[66:67] op_sel_hi:[0,1]
	v_mov_b32_e32 v32, s50
	v_pk_fma_f32 v[26:27], v[32:33], v[22:23], v[26:27] op_sel_hi:[0,1,1] neg_lo:[0,0,1] neg_hi:[0,0,1]
	v_pk_fma_f32 v[28:29], v[32:33], v[24:25], v[28:29] op_sel_hi:[0,1,1] neg_lo:[0,0,1] neg_hi:[0,0,1]
	v_pk_mul_f32 v[26:27], v[10:11], v[26:27]
	v_pk_mul_f32 v[28:29], v[12:13], v[28:29]
	v_cvt_pk_bf16_f32 v30, v26, v27
	v_cvt_pk_bf16_f32 v31, v28, v29
	s_lshl_b32 s47, s47, 11
	v_add_u32_e32 v9, s47, v7
	global_store_dwordx2 v9, v[30:31], s[22:23]
	v_readlane_b32 s36, v6, 2
	v_readlane_b32 s12, v6, 10
	v_pk_mul_f32 v[26:27], s[36:37], v[48:49] op_sel_hi:[0,1]
	v_pk_mul_f32 v[28:29], s[36:37], v[50:51] op_sel_hi:[0,1]
	v_pk_fma_f32 v[26:27], s[12:13], v[80:81], v[26:27] op_sel_hi:[0,1,1] neg_lo:[0,0,1] neg_hi:[0,0,1]
	v_pk_fma_f32 v[28:29], s[12:13], v[82:83], v[28:29] op_sel_hi:[0,1,1] neg_lo:[0,0,1] neg_hi:[0,0,1]
	v_pk_add_f32 v[22:23], v[22:23], v[26:27]
	v_pk_add_f32 v[24:25], v[24:25], v[28:29]
	s_add_i32 s47, s40, 3
	v_readlane_b32 s50, v8, s47
	v_readlane_b32 s36, v6, 7
	v_pk_mul_f32 v[26:27], s[36:37], v[68:69] op_sel_hi:[0,1]
	v_pk_mul_f32 v[28:29], s[36:37], v[70:71] op_sel_hi:[0,1]
	v_mov_b32_e32 v32, s50
	v_pk_fma_f32 v[26:27], v[32:33], v[22:23], v[26:27] op_sel_hi:[0,1,1] neg_lo:[0,0,1] neg_hi:[0,0,1]
	v_pk_fma_f32 v[28:29], v[32:33], v[24:25], v[28:29] op_sel_hi:[0,1,1] neg_lo:[0,0,1] neg_hi:[0,0,1]
	v_pk_mul_f32 v[26:27], v[10:11], v[26:27]
	v_pk_mul_f32 v[28:29], v[12:13], v[28:29]
	v_cvt_pk_bf16_f32 v30, v26, v27
	v_cvt_pk_bf16_f32 v31, v28, v29
	s_lshl_b32 s47, s47, 11
	v_add_u32_e32 v9, s47, v7
	global_store_dwordx2 v9, v[30:31], s[22:23]
	s_branch .Lpz_next
.Lpz_c1:
	s_lshl_b32 s40, s34, 3
	s_lshl_b32 s41, s40, 10
	v_add_u32_e32 v4, s41, v1
	ds_read_b128 v[40:43], v4
	ds_read_b128 v[44:47], v4 offset:1024
	ds_read_b128 v[48:51], v4 offset:2048
	ds_read_b128 v[52:55], v4 offset:3072
	ds_read_b128 v[56:59], v4 offset:4096
	ds_read_b128 v[60:63], v4 offset:5120
	ds_read_b128 v[64:67], v4 offset:6144
	s_waitcnt lgkmcnt(0)
	v_readlane_b32 s36, v5, 0
	v_pk_fma_f32 v[22:23], s[36:37], v[40:41], 0 op_sel_hi:[0,1,0]
	v_pk_fma_f32 v[24:25], s[36:37], v[42:43], 0 op_sel_hi:[0,1,0]
	v_readlane_b32 s12, v5, 1
	v_pk_fma_f32 v[22:23], s[12:13], v[44:45], v[22:23] op_sel_hi:[0,1,1]
	v_pk_fma_f32 v[24:25], s[12:13], v[46:47], v[24:25] op_sel_hi:[0,1,1]
	v_readlane_b32 s36, v5, 2
	v_pk_fma_f32 v[22:23], s[36:37], v[48:49], v[22:23] op_sel_hi:[0,1,1]
	v_pk_fma_f32 v[24:25], s[36:37], v[50:51], v[24:25] op_sel_hi:[0,1,1]
	v_readlane_b32 s12, v5, 3
	v_pk_fma_f32 v[22:23], s[12:13], v[52:53], v[22:23] op_sel_hi:[0,1,1]
	v_pk_fma_f32 v[24:25], s[12:13], v[54:55], v[24:25] op_sel_hi:[0,1,1]
	s_add_i32 s47, s40, 0
	v_readlane_b32 s50, v8, s47
	v_readlane_b32 s36, v5, 2
	v_pk_mul_f32 v[26:27], s[36:37], v[48:49] op_sel_hi:[0,1]
	v_pk_mul_f32 v[28:29], s[36:37], v[50:51] op_sel_hi:[0,1]
	v_mov_b32_e32 v32, s50
	v_pk_fma_f32 v[26:27], v[32:33], v[22:23], v[26:27] op_sel_hi:[0,1,1] neg_lo:[0,0,1] neg_hi:[0,0,1]
	v_pk_fma_f32 v[28:29], v[32:33], v[24:25], v[28:29] op_sel_hi:[0,1,1] neg_lo:[0,0,1] neg_hi:[0,0,1]
	v_pk_mul_f32 v[26:27], v[10:11], v[26:27]
	v_pk_mul_f32 v[28:29], v[12:13], v[28:29]
	v_cvt_pk_bf16_f32 v30, v26, v27
	v_cvt_pk_bf16_f32 v31, v28, v29
	s_lshl_b32 s47, s47, 11
	v_add_u32_e32 v9, s47, v7
	global_store_dwordx2 v9, v[30:31], s[22:23]
	v_readlane_b32 s36, v5, 0
	v_readlane_b32 s12, v5, 4
	v_pk_mul_f32 v[26:27], s[36:37], v[40:41] op_sel_hi:[0,1]
	v_pk_mul_f32 v[28:29], s[36:37], v[42:43] op_sel_hi:[0,1]
	v_pk_fma_f32 v[26:27], s[12:13], v[56:57], v[26:27] op_sel_hi:[0,1,1] neg_lo:[0,0,1] neg_hi:[0,0,1]
	v_pk_fma_f32 v[28:29], s[12:13], v[58:59], v[28:29] op_sel_hi:[0,1,1] neg_lo:[0,0,1] neg_hi:[0,0,1]
	v_pk_add_f32 v[22:23], v[22:23], v[26:27]
	v_pk_add_f32 v[24:25], v[24:25], v[28:29]
	s_add_i32 s47, s40, 1
	v_readlane_b32 s50, v8, s47
	v_readlane_b32 s36, v5, 3
	v_pk_mul_f32 v[26:27], s[36:37], v[52:53] op_sel_hi:[0,1]
	v_pk_mul_f32 v[28:29], s[36:37], v[54:55] op_sel_hi:[0,1]
	v_mov_b32_e32 v32, s50
	v_pk_fma_f32 v[26:27], v[32:33], v[22:23], v[26:27] op_sel_hi:[0,1,1] neg_lo:[0,0,1] neg_hi:[0,0,1]
	v_pk_fma_f32 v[28:29], v[32:33], v[24:25], v[28:29] op_sel_hi:[0,1,1] neg_lo:[0,0,1] neg_hi:[0,0,1]
	v_pk_mul_f32 v[26:27], v[10:11], v[26:27]
	v_pk_mul_f32 v[28:29], v[12:13], v[28:29]
	v_cvt_pk_bf16_f32 v30, v26, v27
	v_cvt_pk_bf16_f32 v31, v28, v29
	s_lshl_b32 s47, s47, 11
	v_add_u32_e32 v9, s47, v7
	global_store_dwordx2 v9, v[30:31], s[22:23]
	v_readlane_b32 s36, v5, 1
	v_readlane_b32 s12, v5, 5
	v_pk_mul_f32 v[26:27], s[36:37], v[44:45] op_sel_hi:[0,1]
	v_pk_mul_f32 v[28:29], s[36:37], v[46:47] op_sel_hi:[0,1]
	v_pk_fma_f32 v[26:27], s[12:13], v[60:61], v[26:27] op_sel_hi:[0,1,1] neg_lo:[0,0,1] neg_hi:[0,0,1]
	v_pk_fma_f32 v[28:29], s[12:13], v[62:63], v[28:29] op_sel_hi:[0,1,1] neg_lo:[0,0,1] neg_hi:[0,0,1]
	v_pk_add_f32 v[22:23], v[22:23], v[26:27]
	v_pk_add_f32 v[24:25], v[24:25], v[28:29]
	s_add_i32 s47, s40, 2
	v_readlane_b32 s50, v8, s47
	v_readlane_b32 s36, v5, 4
	v_pk_mul_f32 v[26:27], s[36:37], v[56:57] op_sel_hi:[0,1]
	v_pk_mul_f32 v[28:29], s[36:37], v[58:59] op_sel_hi:[0,1]
	v_mov_b32_e32 v32, s50
	v_pk_fma_f32 v[26:27], v[32:33], v[22:23], v[26:27] op_sel_hi:[0,1,1] neg_lo:[0,0,1] neg_hi:[0,0,1]
	v_pk_fma_f32 v[28:29], v[32:33], v[24:25], v[28:29] op_sel_hi:[0,1,1] neg_lo:[0,0,1] neg_hi:[0,0,1]
	v_pk_mul_f32 v[26:27], v[10:11], v[26:27]
	v_pk_mul_f32 v[28:29], v[12:13], v[28:29]
	v_cvt_pk_bf16_f32 v30, v26, v27
	v_cvt_pk_bf16_f32 v31, v28, v29
	s_lshl_b32 s47, s47, 11
	v_add_u32_e32 v9, s47, v7
	global_store_dwordx2 v9, v[30:31], s[22:23]
	v_readlane_b32 s36, v5, 2
	v_readlane_b32 s12, v5, 6
	v_pk_mul_f32 v[26:27], s[36:37], v[48:49] op_sel_hi:[0,1]
	v_pk_mul_f32 v[28:29], s[36:37], v[50:51] op_sel_hi:[0,1]
	v_pk_fma_f32 v[26:27], s[12:13], v[64:65], v[26:27] op_sel_hi:[0,1,1] neg_lo:[0,0,1] neg_hi:[0,0,1]
	v_pk_fma_f32 v[28:29], s[12:13], v[66:67], v[28:29] op_sel_hi:[0,1,1] neg_lo:[0,0,1] neg_hi:[0,0,1]
	v_pk_add_f32 v[22:23], v[22:23], v[26:27]
	v_pk_add_f32 v[24:25], v[24:25], v[28:29]
	s_add_i32 s47, s40, 3
	v_readlane_b32 s50, v8, s47
	v_readlane_b32 s36, v5, 5
	v_pk_mul_f32 v[26:27], s[36:37], v[60:61] op_sel_hi:[0,1]
	v_pk_mul_f32 v[28:29], s[36:37], v[62:63] op_sel_hi:[0,1]
	v_mov_b32_e32 v32, s50
	v_pk_fma_f32 v[26:27], v[32:33], v[22:23], v[26:27] op_sel_hi:[0,1,1] neg_lo:[0,0,1] neg_hi:[0,0,1]
	v_pk_fma_f32 v[28:29], v[32:33], v[24:25], v[28:29] op_sel_hi:[0,1,1] neg_lo:[0,0,1] neg_hi:[0,0,1]
	v_pk_mul_f32 v[26:27], v[10:11], v[26:27]
	v_pk_mul_f32 v[28:29], v[12:13], v[28:29]
	v_cvt_pk_bf16_f32 v30, v26, v27
	v_cvt_pk_bf16_f32 v31, v28, v29
	s_lshl_b32 s47, s47, 11
	v_add_u32_e32 v9, s47, v7
	global_store_dwordx2 v9, v[30:31], s[22:23]
	s_lshl_b32 s40, s34, 3
	s_add_i32 s40, s40, 4
	s_lshl_b32 s41, s40, 10
	v_add_u32_e32 v4, s41, v1
	ds_read_b128 v[40:43], v4
	ds_read_b128 v[44:47], v4 offset:1024
	ds_read_b128 v[48:51], v4 offset:2048
	ds_read_b128 v[52:55], v4 offset:3072
	ds_read_b128 v[56:59], v4 offset:4096
	ds_read_b128 v[60:63], v4 offset:5120
	ds_read_b128 v[64:67], v4 offset:6144
	s_waitcnt lgkmcnt(0)
	v_readlane_b32 s36, v6, 0
	v_pk_fma_f32 v[22:23], s[36:37], v[40:41], 0 op_sel_hi:[0,1,0]
	v_pk_fma_f32 v[24:25], s[36:37], v[42:43], 0 op_sel_hi:[0,1,0]
	v_readlane_b32 s12, v6, 1
	v_pk_fma_f32 v[22:23], s[12:13], v[44:45], v[22:23] op_sel_hi:[0,1,1]
	v_pk_fma_f32 v[24:25], s[12:13], v[46:47], v[24:25] op_sel_hi:[0,1,1]
	v_readlane_b32 s36, v6, 2
	v_pk_fma_f32 v[22:23], s[36:37], v[48:49], v[22:23] op_sel_hi:[0,1,1]
	v_pk_fma_f32 v[24:25], s[36:37], v[50:51], v[24:25] op_sel_hi:[0,1,1]
	v_readlane_b32 s12, v6, 3
	v_pk_fma_f32 v[22:23], s[12:13], v[52:53], v[22:23] op_sel_hi:[0,1,1]
	v_pk_fma_f32 v[24:25], s[12:13], v[54:55], v[24:25] op_sel_hi:[0,1,1]
	s_add_i32 s47, s40, 0
	v_readlane_b32 s50, v8, s47
	v_readlane_b32 s36, v6, 2
	v_pk_mul_f32 v[26:27], s[36:37], v[48:49] op_sel_hi:[0,1]
	v_pk_mul_f32 v[28:29], s[36:37], v[50:51] op_sel_hi:[0,1]
	v_mov_b32_e32 v32, s50
	v_pk_fma_f32 v[26:27], v[32:33], v[22:23], v[26:27] op_sel_hi:[0,1,1] neg_lo:[0,0,1] neg_hi:[0,0,1]
	v_pk_fma_f32 v[28:29], v[32:33], v[24:25], v[28:29] op_sel_hi:[0,1,1] neg_lo:[0,0,1] neg_hi:[0,0,1]
	v_pk_mul_f32 v[26:27], v[10:11], v[26:27]
	v_pk_mul_f32 v[28:29], v[12:13], v[28:29]
	v_cvt_pk_bf16_f32 v30, v26, v27
	v_cvt_pk_bf16_f32 v31, v28, v29
	s_lshl_b32 s47, s47, 11
	v_add_u32_e32 v9, s47, v7
	global_store_dwordx2 v9, v[30:31], s[22:23]
	v_readlane_b32 s36, v6, 0
	v_readlane_b32 s12, v6, 4
	v_pk_mul_f32 v[26:27], s[36:37], v[40:41] op_sel_hi:[0,1]
	v_pk_mul_f32 v[28:29], s[36:37], v[42:43] op_sel_hi:[0,1]
	v_pk_fma_f32 v[26:27], s[12:13], v[56:57], v[26:27] op_sel_hi:[0,1,1] neg_lo:[0,0,1] neg_hi:[0,0,1]
	v_pk_fma_f32 v[28:29], s[12:13], v[58:59], v[28:29] op_sel_hi:[0,1,1] neg_lo:[0,0,1] neg_hi:[0,0,1]
	v_pk_add_f32 v[22:23], v[22:23], v[26:27]
	v_pk_add_f32 v[24:25], v[24:25], v[28:29]
	s_add_i32 s47, s40, 1
	v_readlane_b32 s50, v8, s47
	v_readlane_b32 s36, v6, 3
	v_pk_mul_f32 v[26:27], s[36:37], v[52:53] op_sel_hi:[0,1]
	v_pk_mul_f32 v[28:29], s[36:37], v[54:55] op_sel_hi:[0,1]
	v_mov_b32_e32 v32, s50
	v_pk_fma_f32 v[26:27], v[32:33], v[22:23], v[26:27] op_sel_hi:[0,1,1] neg_lo:[0,0,1] neg_hi:[0,0,1]
	v_pk_fma_f32 v[28:29], v[32:33], v[24:25], v[28:29] op_sel_hi:[0,1,1] neg_lo:[0,0,1] neg_hi:[0,0,1]
	v_pk_mul_f32 v[26:27], v[10:11], v[26:27]
	v_pk_mul_f32 v[28:29], v[12:13], v[28:29]
	v_cvt_pk_bf16_f32 v30, v26, v27
	v_cvt_pk_bf16_f32 v31, v28, v29
	s_lshl_b32 s47, s47, 11
	v_add_u32_e32 v9, s47, v7
	global_store_dwordx2 v9, v[30:31], s[22:23]
	v_readlane_b32 s36, v6, 1
	v_readlane_b32 s12, v6, 5
	v_pk_mul_f32 v[26:27], s[36:37], v[44:45] op_sel_hi:[0,1]
	v_pk_mul_f32 v[28:29], s[36:37], v[46:47] op_sel_hi:[0,1]
	v_pk_fma_f32 v[26:27], s[12:13], v[60:61], v[26:27] op_sel_hi:[0,1,1] neg_lo:[0,0,1] neg_hi:[0,0,1]
	v_pk_fma_f32 v[28:29], s[12:13], v[62:63], v[28:29] op_sel_hi:[0,1,1] neg_lo:[0,0,1] neg_hi:[0,0,1]
	v_pk_add_f32 v[22:23], v[22:23], v[26:27]
	v_pk_add_f32 v[24:25], v[24:25], v[28:29]
	s_add_i32 s47, s40, 2
	v_readlane_b32 s50, v8, s47
	v_readlane_b32 s36, v6, 4
	v_pk_mul_f32 v[26:27], s[36:37], v[56:57] op_sel_hi:[0,1]
	v_pk_mul_f32 v[28:29], s[36:37], v[58:59] op_sel_hi:[0,1]
	v_mov_b32_e32 v32, s50
	v_pk_fma_f32 v[26:27], v[32:33], v[22:23], v[26:27] op_sel_hi:[0,1,1] neg_lo:[0,0,1] neg_hi:[0,0,1]
	v_pk_fma_f32 v[28:29], v[32:33], v[24:25], v[28:29] op_sel_hi:[0,1,1] neg_lo:[0,0,1] neg_hi:[0,0,1]
	v_pk_mul_f32 v[26:27], v[10:11], v[26:27]
	v_pk_mul_f32 v[28:29], v[12:13], v[28:29]
	v_cvt_pk_bf16_f32 v30, v26, v27
	v_cvt_pk_bf16_f32 v31, v28, v29
	s_lshl_b32 s47, s47, 11
	v_add_u32_e32 v9, s47, v7
	global_store_dwordx2 v9, v[30:31], s[22:23]
	v_readlane_b32 s36, v6, 2
	v_readlane_b32 s12, v6, 6
	v_pk_mul_f32 v[26:27], s[36:37], v[48:49] op_sel_hi:[0,1]
	v_pk_mul_f32 v[28:29], s[36:37], v[50:51] op_sel_hi:[0,1]
	v_pk_fma_f32 v[26:27], s[12:13], v[64:65], v[26:27] op_sel_hi:[0,1,1] neg_lo:[0,0,1] neg_hi:[0,0,1]
	v_pk_fma_f32 v[28:29], s[12:13], v[66:67], v[28:29] op_sel_hi:[0,1,1] neg_lo:[0,0,1] neg_hi:[0,0,1]
	v_pk_add_f32 v[22:23], v[22:23], v[26:27]
	v_pk_add_f32 v[24:25], v[24:25], v[28:29]
	s_add_i32 s47, s40, 3
	v_readlane_b32 s50, v8, s47
	v_readlane_b32 s36, v6, 5
	v_pk_mul_f32 v[26:27], s[36:37], v[60:61] op_sel_hi:[0,1]
	v_pk_mul_f32 v[28:29], s[36:37], v[62:63] op_sel_hi:[0,1]
	v_mov_b32_e32 v32, s50
	v_pk_fma_f32 v[26:27], v[32:33], v[22:23], v[26:27] op_sel_hi:[0,1,1] neg_lo:[0,0,1] neg_hi:[0,0,1]
	v_pk_fma_f32 v[28:29], v[32:33], v[24:25], v[28:29] op_sel_hi:[0,1,1] neg_lo:[0,0,1] neg_hi:[0,0,1]
	v_pk_mul_f32 v[26:27], v[10:11], v[26:27]
	v_pk_mul_f32 v[28:29], v[12:13], v[28:29]
	v_cvt_pk_bf16_f32 v30, v26, v27
	v_cvt_pk_bf16_f32 v31, v28, v29
	s_lshl_b32 s47, s47, 11
	v_add_u32_e32 v9, s47, v7
	global_store_dwordx2 v9, v[30:31], s[22:23]
	s_branch .Lpz_next
.Lpz_c0:
	s_lshl_b32 s40, s34, 3
	s_lshl_b32 s41, s40, 10
	v_add_u32_e32 v4, s41, v1
	ds_read_b128 v[40:43], v4
	ds_read_b128 v[44:47], v4 offset:1024
	ds_read_b128 v[48:51], v4 offset:2048
	ds_read_b128 v[52:55], v4 offset:3072
	ds_read_b128 v[56:59], v4 offset:4096
	s_waitcnt lgkmcnt(0)
	v_readlane_b32 s36, v5, 0
	v_pk_fma_f32 v[22:23], s[36:37], v[40:41], 0 op_sel_hi:[0,1,0]
	v_pk_fma_f32 v[24:25], s[36:37], v[42:43], 0 op_sel_hi:[0,1,0]
	v_readlane_b32 s12, v5, 1
	v_pk_fma_f32 v[22:23], s[12:13], v[44:45], v[22:23] op_sel_hi:[0,1,1]
	v_pk_fma_f32 v[24:25], s[12:13], v[46:47], v[24:25] op_sel_hi:[0,1,1]
	s_add_i32 s47, s40, 0
	v_readlane_b32 s50, v8, s47
	v_readlane_b32 s36, v5, 1
	v_pk_mul_f32 v[26:27], s[36:37], v[44:45] op_sel_hi:[0,1]
	v_pk_mul_f32 v[28:29], s[36:37], v[46:47] op_sel_hi:[0,1]
	v_mov_b32_e32 v32, s50
	v_pk_fma_f32 v[26:27], v[32:33], v[22:23], v[26:27] op_sel_hi:[0,1,1] neg_lo:[0,0,1] neg_hi:[0,0,1]
	v_pk_fma_f32 v[28:29], v[32:33], v[24:25], v[28:29] op_sel_hi:[0,1,1] neg_lo:[0,0,1] neg_hi:[0,0,1]
	v_pk_mul_f32 v[26:27], v[10:11], v[26:27]
	v_pk_mul_f32 v[28:29], v[12:13], v[28:29]
	v_cvt_pk_bf16_f32 v30, v26, v27
	v_cvt_pk_bf16_f32 v31, v28, v29
	s_lshl_b32 s47, s47, 11
	v_add_u32_e32 v9, s47, v7
	global_store_dwordx2 v9, v[30:31], s[22:23]
	v_readlane_b32 s36, v5, 0
	v_readlane_b32 s12, v5, 2
	v_pk_mul_f32 v[26:27], s[36:37], v[40:41] op_sel_hi:[0,1]
	v_pk_mul_f32 v[28:29], s[36:37], v[42:43] op_sel_hi:[0,1]
	v_pk_fma_f32 v[26:27], s[12:13], v[48:49], v[26:27] op_sel_hi:[0,1,1] neg_lo:[0,0,1] neg_hi:[0,0,1]
	v_pk_fma_f32 v[28:29], s[12:13], v[50:51], v[28:29] op_sel_hi:[0,1,1] neg_lo:[0,0,1] neg_hi:[0,0,1]
	v_pk_add_f32 v[22:23], v[22:23], v[26:27]
	v_pk_add_f32 v[24:25], v[24:25], v[28:29]
	s_add_i32 s47, s40, 1
	v_readlane_b32 s50, v8, s47
	v_readlane_b32 s36, v5, 2
	v_pk_mul_f32 v[26:27], s[36:37], v[48:49] op_sel_hi:[0,1]
	v_pk_mul_f32 v[28:29], s[36:37], v[50:51] op_sel_hi:[0,1]
	v_mov_b32_e32 v32, s50
	v_pk_fma_f32 v[26:27], v[32:33], v[22:23], v[26:27] op_sel_hi:[0,1,1] neg_lo:[0,0,1] neg_hi:[0,0,1]
	v_pk_fma_f32 v[28:29], v[32:33], v[24:25], v[28:29] op_sel_hi:[0,1,1] neg_lo:[0,0,1] neg_hi:[0,0,1]
	v_pk_mul_f32 v[26:27], v[10:11], v[26:27]
	v_pk_mul_f32 v[28:29], v[12:13], v[28:29]
	v_cvt_pk_bf16_f32 v30, v26, v27
	v_cvt_pk_bf16_f32 v31, v28, v29
	s_lshl_b32 s47, s47, 11
	v_add_u32_e32 v9, s47, v7
	global_store_dwordx2 v9, v[30:31], s[22:23]
	v_readlane_b32 s36, v5, 1
	v_readlane_b32 s12, v5, 3
	v_pk_mul_f32 v[26:27], s[36:37], v[44:45] op_sel_hi:[0,1]
	v_pk_mul_f32 v[28:29], s[36:37], v[46:47] op_sel_hi:[0,1]
	v_pk_fma_f32 v[26:27], s[12:13], v[52:53], v[26:27] op_sel_hi:[0,1,1] neg_lo:[0,0,1] neg_hi:[0,0,1]
	v_pk_fma_f32 v[28:29], s[12:13], v[54:55], v[28:29] op_sel_hi:[0,1,1] neg_lo:[0,0,1] neg_hi:[0,0,1]
	v_pk_add_f32 v[22:23], v[22:23], v[26:27]
	v_pk_add_f32 v[24:25], v[24:25], v[28:29]
	s_add_i32 s47, s40, 2
	v_readlane_b32 s50, v8, s47
	v_readlane_b32 s36, v5, 3
	v_pk_mul_f32 v[26:27], s[36:37], v[52:53] op_sel_hi:[0,1]
	v_pk_mul_f32 v[28:29], s[36:37], v[54:55] op_sel_hi:[0,1]
	v_mov_b32_e32 v32, s50
	v_pk_fma_f32 v[26:27], v[32:33], v[22:23], v[26:27] op_sel_hi:[0,1,1] neg_lo:[0,0,1] neg_hi:[0,0,1]
	v_pk_fma_f32 v[28:29], v[32:33], v[24:25], v[28:29] op_sel_hi:[0,1,1] neg_lo:[0,0,1] neg_hi:[0,0,1]
	v_pk_mul_f32 v[26:27], v[10:11], v[26:27]
	v_pk_mul_f32 v[28:29], v[12:13], v[28:29]
	v_cvt_pk_bf16_f32 v30, v26, v27
	v_cvt_pk_bf16_f32 v31, v28, v29
	s_lshl_b32 s47, s47, 11
	v_add_u32_e32 v9, s47, v7
	global_store_dwordx2 v9, v[30:31], s[22:23]
	v_readlane_b32 s36, v5, 2
	v_readlane_b32 s12, v5, 4
	v_pk_mul_f32 v[26:27], s[36:37], v[48:49] op_sel_hi:[0,1]
	v_pk_mul_f32 v[28:29], s[36:37], v[50:51] op_sel_hi:[0,1]
	v_pk_fma_f32 v[26:27], s[12:13], v[56:57], v[26:27] op_sel_hi:[0,1,1] neg_lo:[0,0,1] neg_hi:[0,0,1]
	v_pk_fma_f32 v[28:29], s[12:13], v[58:59], v[28:29] op_sel_hi:[0,1,1] neg_lo:[0,0,1] neg_hi:[0,0,1]
	v_pk_add_f32 v[22:23], v[22:23], v[26:27]
	v_pk_add_f32 v[24:25], v[24:25], v[28:29]
	s_add_i32 s47, s40, 3
	v_readlane_b32 s50, v8, s47
	v_readlane_b32 s36, v5, 4
	v_pk_mul_f32 v[26:27], s[36:37], v[56:57] op_sel_hi:[0,1]
	v_pk_mul_f32 v[28:29], s[36:37], v[58:59] op_sel_hi:[0,1]
	v_mov_b32_e32 v32, s50
	v_pk_fma_f32 v[26:27], v[32:33], v[22:23], v[26:27] op_sel_hi:[0,1,1] neg_lo:[0,0,1] neg_hi:[0,0,1]
	v_pk_fma_f32 v[28:29], v[32:33], v[24:25], v[28:29] op_sel_hi:[0,1,1] neg_lo:[0,0,1] neg_hi:[0,0,1]
	v_pk_mul_f32 v[26:27], v[10:11], v[26:27]
	v_pk_mul_f32 v[28:29], v[12:13], v[28:29]
	v_cvt_pk_bf16_f32 v30, v26, v27
	v_cvt_pk_bf16_f32 v31, v28, v29
	s_lshl_b32 s47, s47, 11
	v_add_u32_e32 v9, s47, v7
	global_store_dwordx2 v9, v[30:31], s[22:23]
	s_lshl_b32 s40, s34, 3
	s_add_i32 s40, s40, 4
	s_lshl_b32 s41, s40, 10
	v_add_u32_e32 v4, s41, v1
	ds_read_b128 v[40:43], v4
	ds_read_b128 v[44:47], v4 offset:1024
	ds_read_b128 v[48:51], v4 offset:2048
	ds_read_b128 v[52:55], v4 offset:3072
	ds_read_b128 v[56:59], v4 offset:4096
	s_waitcnt lgkmcnt(0)
	v_readlane_b32 s36, v6, 0
	v_pk_fma_f32 v[22:23], s[36:37], v[40:41], 0 op_sel_hi:[0,1,0]
	v_pk_fma_f32 v[24:25], s[36:37], v[42:43], 0 op_sel_hi:[0,1,0]
	v_readlane_b32 s12, v6, 1
	v_pk_fma_f32 v[22:23], s[12:13], v[44:45], v[22:23] op_sel_hi:[0,1,1]
	v_pk_fma_f32 v[24:25], s[12:13], v[46:47], v[24:25] op_sel_hi:[0,1,1]
	s_add_i32 s47, s40, 0
	v_readlane_b32 s50, v8, s47
	v_readlane_b32 s36, v6, 1
	v_pk_mul_f32 v[26:27], s[36:37], v[44:45] op_sel_hi:[0,1]
	v_pk_mul_f32 v[28:29], s[36:37], v[46:47] op_sel_hi:[0,1]
	v_mov_b32_e32 v32, s50
	v_pk_fma_f32 v[26:27], v[32:33], v[22:23], v[26:27] op_sel_hi:[0,1,1] neg_lo:[0,0,1] neg_hi:[0,0,1]
	v_pk_fma_f32 v[28:29], v[32:33], v[24:25], v[28:29] op_sel_hi:[0,1,1] neg_lo:[0,0,1] neg_hi:[0,0,1]
	v_pk_mul_f32 v[26:27], v[10:11], v[26:27]
	v_pk_mul_f32 v[28:29], v[12:13], v[28:29]
	v_cvt_pk_bf16_f32 v30, v26, v27
	v_cvt_pk_bf16_f32 v31, v28, v29
	s_lshl_b32 s47, s47, 11
	v_add_u32_e32 v9, s47, v7
	global_store_dwordx2 v9, v[30:31], s[22:23]
	v_readlane_b32 s36, v6, 0
	v_readlane_b32 s12, v6, 2
	v_pk_mul_f32 v[26:27], s[36:37], v[40:41] op_sel_hi:[0,1]
	v_pk_mul_f32 v[28:29], s[36:37], v[42:43] op_sel_hi:[0,1]
	v_pk_fma_f32 v[26:27], s[12:13], v[48:49], v[26:27] op_sel_hi:[0,1,1] neg_lo:[0,0,1] neg_hi:[0,0,1]
	v_pk_fma_f32 v[28:29], s[12:13], v[50:51], v[28:29] op_sel_hi:[0,1,1] neg_lo:[0,0,1] neg_hi:[0,0,1]
	v_pk_add_f32 v[22:23], v[22:23], v[26:27]
	v_pk_add_f32 v[24:25], v[24:25], v[28:29]
	s_add_i32 s47, s40, 1
	v_readlane_b32 s50, v8, s47
	v_readlane_b32 s36, v6, 2
	v_pk_mul_f32 v[26:27], s[36:37], v[48:49] op_sel_hi:[0,1]
	v_pk_mul_f32 v[28:29], s[36:37], v[50:51] op_sel_hi:[0,1]
	v_mov_b32_e32 v32, s50
	v_pk_fma_f32 v[26:27], v[32:33], v[22:23], v[26:27] op_sel_hi:[0,1,1] neg_lo:[0,0,1] neg_hi:[0,0,1]
	v_pk_fma_f32 v[28:29], v[32:33], v[24:25], v[28:29] op_sel_hi:[0,1,1] neg_lo:[0,0,1] neg_hi:[0,0,1]
	v_pk_mul_f32 v[26:27], v[10:11], v[26:27]
	v_pk_mul_f32 v[28:29], v[12:13], v[28:29]
	v_cvt_pk_bf16_f32 v30, v26, v27
	v_cvt_pk_bf16_f32 v31, v28, v29
	s_lshl_b32 s47, s47, 11
	v_add_u32_e32 v9, s47, v7
	global_store_dwordx2 v9, v[30:31], s[22:23]
	v_readlane_b32 s36, v6, 1
	v_readlane_b32 s12, v6, 3
	v_pk_mul_f32 v[26:27], s[36:37], v[44:45] op_sel_hi:[0,1]
	v_pk_mul_f32 v[28:29], s[36:37], v[46:47] op_sel_hi:[0,1]
	v_pk_fma_f32 v[26:27], s[12:13], v[52:53], v[26:27] op_sel_hi:[0,1,1] neg_lo:[0,0,1] neg_hi:[0,0,1]
	v_pk_fma_f32 v[28:29], s[12:13], v[54:55], v[28:29] op_sel_hi:[0,1,1] neg_lo:[0,0,1] neg_hi:[0,0,1]
	v_pk_add_f32 v[22:23], v[22:23], v[26:27]
	v_pk_add_f32 v[24:25], v[24:25], v[28:29]
	s_add_i32 s47, s40, 2
	v_readlane_b32 s50, v8, s47
	v_readlane_b32 s36, v6, 3
	v_pk_mul_f32 v[26:27], s[36:37], v[52:53] op_sel_hi:[0,1]
	v_pk_mul_f32 v[28:29], s[36:37], v[54:55] op_sel_hi:[0,1]
	v_mov_b32_e32 v32, s50
	v_pk_fma_f32 v[26:27], v[32:33], v[22:23], v[26:27] op_sel_hi:[0,1,1] neg_lo:[0,0,1] neg_hi:[0,0,1]
	v_pk_fma_f32 v[28:29], v[32:33], v[24:25], v[28:29] op_sel_hi:[0,1,1] neg_lo:[0,0,1] neg_hi:[0,0,1]
	v_pk_mul_f32 v[26:27], v[10:11], v[26:27]
	v_pk_mul_f32 v[28:29], v[12:13], v[28:29]
	v_cvt_pk_bf16_f32 v30, v26, v27
	v_cvt_pk_bf16_f32 v31, v28, v29
	s_lshl_b32 s47, s47, 11
	v_add_u32_e32 v9, s47, v7
	global_store_dwordx2 v9, v[30:31], s[22:23]
	v_readlane_b32 s36, v6, 2
	v_readlane_b32 s12, v6, 4
	v_pk_mul_f32 v[26:27], s[36:37], v[48:49] op_sel_hi:[0,1]
	v_pk_mul_f32 v[28:29], s[36:37], v[50:51] op_sel_hi:[0,1]
	v_pk_fma_f32 v[26:27], s[12:13], v[56:57], v[26:27] op_sel_hi:[0,1,1] neg_lo:[0,0,1] neg_hi:[0,0,1]
	v_pk_fma_f32 v[28:29], s[12:13], v[58:59], v[28:29] op_sel_hi:[0,1,1] neg_lo:[0,0,1] neg_hi:[0,0,1]
	v_pk_add_f32 v[22:23], v[22:23], v[26:27]
	v_pk_add_f32 v[24:25], v[24:25], v[28:29]
	s_add_i32 s47, s40, 3
	v_readlane_b32 s50, v8, s47
	v_readlane_b32 s36, v6, 4
	v_pk_mul_f32 v[26:27], s[36:37], v[56:57] op_sel_hi:[0,1]
	v_pk_mul_f32 v[28:29], s[36:37], v[58:59] op_sel_hi:[0,1]
	v_mov_b32_e32 v32, s50
	v_pk_fma_f32 v[26:27], v[32:33], v[22:23], v[26:27] op_sel_hi:[0,1,1] neg_lo:[0,0,1] neg_hi:[0,0,1]
	v_pk_fma_f32 v[28:29], v[32:33], v[24:25], v[28:29] op_sel_hi:[0,1,1] neg_lo:[0,0,1] neg_hi:[0,0,1]
	v_pk_mul_f32 v[26:27], v[10:11], v[26:27]
	v_pk_mul_f32 v[28:29], v[12:13], v[28:29]
	v_cvt_pk_bf16_f32 v30, v26, v27
	v_cvt_pk_bf16_f32 v31, v28, v29
	s_lshl_b32 s47, s47, 11
	v_add_u32_e32 v9, s47, v7
	global_store_dwordx2 v9, v[30:31], s[22:23]
.Lpz_next:
	s_barrier
	s_cmp_lt_u32 s24, 0x300
	s_cbranch_scc1 .Lpz_tile
	s_mov_b64 exec, s[14:15]
